# v47: v46 + up-front A-fragment LDS reads also in RG-LRU pass 2's peeled first tile
# speedup vs baseline: 1.0125x; 1.0041x over previous
.LBB0_598:
	v_mad_u32_u24 v97, v116, s3, v149
	ds_read_b128 v[98:101], v97
	ds_read_b128 v[92:95], v97 offset:64
	ds_read_b128 v[228:231], v97 offset:128
	ds_read_b128 v[232:235], v97 offset:192
	v_add_u32_e32 v117, s14, v161
	v_add_u32_e32 v171, 0xec00, v117
	v_add_u32_e32 v176, 0xf000, v117
	s_waitcnt lgkmcnt(3)
	v_mfma_f32_16x16x32_bf16 v[172:175], v[98:101], v[16:19], 0
	s_addk_i32 s14, 0xdf00
	v_add_u32_e32 v116, -16, v116
	v_add_u32_e32 v195, 0x1f700, v117
	v_mfma_f32_16x16x32_bf16 v[102:105], v[98:101], v[0:3], 0
	v_add_u32_e32 v206, 0x1fd30, v117
	v_add_u32_e32 v207, 0x1fb20, v117
	v_add_u32_e32 v208, 0x1f910, v117
	v_mfma_f32_16x16x32_bf16 v[110:113], v[98:101], v[32:35], 0
	v_add_u32_e32 v209, 0x1fd70, v117
	v_add_u32_e32 v210, 0x1fb60, v117
	v_add_u32_e32 v211, 0x1f950, v117
	v_mfma_f32_16x16x32_bf16 v[106:109], v[98:101], v[48:51], 0
	s_cmp_lg_u32 s14, 0xffff7c00
	s_waitcnt lgkmcnt(2)
	v_mfma_f32_16x16x32_bf16 v[98:101], v[92:95], v[20:23], v[172:175]
	v_mfma_f32_16x16x32_bf16 v[102:105], v[92:95], v[4:7], v[102:105]
	v_mfma_f32_16x16x32_bf16 v[110:113], v[92:95], v[36:39], v[110:113]
	v_mfma_f32_16x16x32_bf16 v[92:95], v[92:95], v[52:55], v[106:109]
	s_waitcnt lgkmcnt(1)
	v_mfma_f32_16x16x32_bf16 v[102:105], v[228:231], v[8:11], v[102:105]
	v_add_u32_e32 v97, 0xe800, v117
	v_add_u32_e32 v117, 0x1f740, v117
	v_mfma_f32_16x16x32_bf16 v[110:113], v[228:231], v[40:43], v[110:113]
	v_mfma_f32_16x16x32_bf16 v[98:101], v[228:231], v[24:27], v[98:101]
	v_mfma_f32_16x16x32_bf16 v[92:95], v[228:231], v[56:59], v[92:95]
	ds_read2_b32 v[172:173], v176 offset0:76 offset1:92
	ds_read2_b32 v[174:175], v171 offset0:200 offset1:216
	ds_read2_b32 v[176:177], v171 offset0:68 offset1:84
	ds_read2_b32 v[178:179], v97 offset0:192 offset1:208
	s_waitcnt lgkmcnt(3)
	v_mov_b32_e32 v181, v172
	v_mfma_f32_16x16x32_bf16 v[102:105], v[232:235], v[12:15], v[102:105]
	s_waitcnt lgkmcnt(2)
	v_mov_b32_e32 v182, v175
	s_waitcnt lgkmcnt(0)
	v_mov_b32_e32 v186, v179
	v_mov_b32_e32 v184, v177
	v_mfma_f32_16x16x32_bf16 v[110:113], v[232:235], v[44:47], v[110:113]
	v_mfma_f32_16x16x32_bf16 v[98:101], v[232:235], v[28:31], v[98:101]
	s_nop 0
	v_fmamk_f32 v97, v102, 0xbfb8aa3b, v163
	s_nop 4
	v_fmamk_f32 v102, v110, 0xbfb8aa3b, v164
	v_fmamk_f32 v103, v103, 0xbfb8aa3b, v163
	v_mfma_f32_16x16x32_bf16 v[92:95], v[232:235], v[60:63], v[92:95]
	v_fmamk_f32 v104, v104, 0xbfb8aa3b, v163
	v_fmamk_f32 v105, v105, 0xbfb8aa3b, v163
	v_fmamk_f32 v98, v98, 0xbfb8aa3b, v168
	v_fmamk_f32 v99, v99, 0xbfb8aa3b, v168
	v_fmamk_f32 v100, v100, 0xbfb8aa3b, v168
	s_nop 2
	v_fmamk_f32 v92, v92, 0xbfb8aa3b, v167
	s_nop 0
	s_nop 0
	s_nop 0
	s_nop 0
	s_nop 0
	v_fmamk_f32 v94, v94, 0xbfb8aa3b, v167
	v_fmamk_f32 v101, v101, 0xbfb8aa3b, v168
	s_nop 0
	s_nop 0
	s_nop 0
	s_nop 0
	v_exp_f32_e32 v97, v97
	v_exp_f32_e32 v102, v102
	v_exp_f32_e32 v103, v103
	v_exp_f32_e32 v104, v104
	v_exp_f32_e32 v105, v105
	v_exp_f32_e32 v98, v98
	v_exp_f32_e32 v92, v92
	v_exp_f32_e32 v99, v99
	v_exp_f32_e32 v100, v100
	v_fmamk_f32 v95, v95, 0xbfb8aa3b, v167
	v_exp_f32_e32 v94, v94
	v_exp_f32_e32 v101, v101
	v_exp_f32_e32 v95, v95
	v_add_f32_e32 v97, 1.0, v97
	v_add_f32_e32 v102, 1.0, v102
	v_add_f32_e32 v103, 1.0, v103
	v_add_f32_e32 v104, 1.0, v104
	v_add_f32_e32 v105, 1.0, v105
	v_add_f32_e32 v98, 1.0, v98
	v_add_f32_e32 v92, 1.0, v92
	v_add_f32_e32 v99, 1.0, v99
	v_add_f32_e32 v100, 1.0, v100
	v_rcp_f32_e32 v97, v97
	v_rcp_f32_e32 v109, v102
	v_rcp_f32_e32 v102, v103
	v_rcp_f32_e32 v103, v104
	v_rcp_f32_e32 v104, v105
	v_add_f32_e32 v94, 1.0, v94
	v_add_f32_e32 v101, 1.0, v101
	v_rcp_f32_e32 v98, v98
	v_rcp_f32_e32 v110, v92
	v_rcp_f32_e32 v92, v99
	v_rcp_f32_e32 v99, v100
	v_fmamk_f32 v106, v111, 0xbfb8aa3b, v164
	v_rcp_f32_e32 v111, v94
	v_rcp_f32_e32 v94, v101
	v_add_f32_e32 v95, 1.0, v95
	v_fmamk_f32 v108, v113, 0xbfb8aa3b, v164
	v_rcp_f32_e32 v113, v95
	v_mul_f32_e32 v95, v97, v165
	v_mul_f32_e32 v100, v103, v165
	v_mul_f32_e32 v101, v104, v165
	v_fmamk_f32 v107, v112, 0xbfb8aa3b, v164
	v_mul_f32_e32 v97, v102, v165
	v_mul_f32_e32 v98, v98, v166
	v_mul_f32_e32 v92, v92, v166
	v_mul_f32_e32 v99, v99, v166
	v_fmamk_f32 v93, v93, 0xbfb8aa3b, v167
	v_mul_f32_e32 v94, v94, v166
	v_exp_f32_e32 v179, v95
	v_exp_f32_e32 v175, v100
	v_exp_f32_e32 v180, v101
	v_exp_f32_e32 v107, v107
	v_exp_f32_e32 v108, v108
	v_exp_f32_e32 v177, v97
	v_exp_f32_e32 v187, v98
	v_exp_f32_e32 v185, v92
	v_exp_f32_e32 v183, v99
	v_exp_f32_e32 v106, v106
	v_exp_f32_e32 v93, v93
	v_exp_f32_e32 v92, v94
	v_fma_f32 v94, -v179, v179, 1.0
	v_fma_f32 v97, -v175, v175, 1.0
	v_fma_f32 v98, -v180, v180, 1.0
	v_add_f32_e32 v107, 1.0, v107
	v_add_f32_e32 v108, 1.0, v108
	v_fma_f32 v95, -v177, v177, 1.0
	v_fma_f32 v100, -v187, v187, 1.0
	v_fma_f32 v101, -v185, v185, 1.0
	v_fma_f32 v102, -v183, v183, 1.0
	v_max_f32_e32 v94, 0, v94
	v_max_f32_e32 v97, 0, v97
	v_max_f32_e32 v98, 0, v98
	v_add_f32_e32 v106, 1.0, v106
	v_add_f32_e32 v93, 1.0, v93
	v_rcp_f32_e32 v107, v107
	v_rcp_f32_e32 v105, v108
	v_fma_f32 v103, -v92, v92, 1.0
	v_max_f32_e32 v95, 0, v95
	v_max_f32_e32 v100, 0, v100
	v_max_f32_e32 v101, 0, v101
	v_max_f32_e32 v102, 0, v102
	v_sqrt_f32_e32 v108, v94
	v_sqrt_f32_e32 v97, v97
	v_sqrt_f32_e32 v171, v98
	v_rcp_f32_e32 v106, v106
	v_rcp_f32_e32 v93, v93
	v_max_f32_e32 v103, 0, v103
	v_sqrt_f32_e32 v112, v95
	v_sqrt_f32_e32 v172, v100
	v_sqrt_f32_e32 v188, v101
	v_sqrt_f32_e32 v189, v102
	v_mul_f32_e32 v104, v92, v183
	v_sqrt_f32_e32 v190, v103
	v_mul_f32_e32 v104, v185, v104
	v_mul_f32_e32 v103, v187, v104
	v_mul_f32_e32 v104, v109, v108
	v_mul_f32_e32 v108, v107, v97
	v_mul_f32_e32 v97, v105, v171
	v_mul_f32_e32 v106, v106, v112
	v_mul_f32_e32 v110, v110, v172
	v_mul_f32_e32 v112, v93, v188
	v_mul_f32_e32 v172, v111, v189
	v_pk_mul_f32 v[188:189], v[180:181], v[96:97]
	v_mul_f32_e32 v93, v113, v190
	v_pk_fma_f32 v[190:191], v[180:181], v[96:97], v[188:189] op_sel_hi:[1,1,0]
	v_mov_b32_e32 v97, v173
	v_mov_b32_e32 v109, v191
	v_pk_mul_f32 v[190:191], v[92:93], v[96:97]
	v_pk_mul_f32 v[192:193], v[174:175], v[108:109]
	v_pk_fma_f32 v[198:199], v[92:93], v[96:97], v[190:191] op_sel_hi:[1,1,0]
	v_pk_fma_f32 v[108:109], v[174:175], v[108:109], v[192:193] op_sel_hi:[1,1,0]
	v_mov_b32_e32 v173, v199
	v_mov_b32_e32 v107, v109
	v_pk_mul_f32 v[108:109], v[172:173], v[182:183]
	v_pk_mul_f32 v[198:199], v[176:177], v[106:107]
	v_pk_fma_f32 v[172:173], v[172:173], v[182:183], v[108:109] op_sel_hi:[1,1,0]
	v_pk_fma_f32 v[106:107], v[176:177], v[106:107], v[198:199] op_sel_hi:[1,1,0]
	v_mov_b32_e32 v113, v173
	v_mov_b32_e32 v105, v107
	v_pk_mul_f32 v[106:107], v[112:113], v[184:185]
	v_mul_f32_e32 v99, v180, v175
	v_pk_fma_f32 v[112:113], v[112:113], v[184:185], v[106:107] op_sel_hi:[1,1,0]
	v_mul_f32_e32 v99, v177, v99
	v_mov_b32_e32 v111, v113
	v_pk_mul_f32 v[172:173], v[178:179], v[104:105]
	v_pk_mul_f32 v[204:205], v[110:111], v[186:187]
	v_mul_f32_e32 v95, v179, v99
	v_pk_fma_f32 v[104:105], v[178:179], v[104:105], v[172:173] op_sel:[0,0,1] op_sel_hi:[1,1,0]
	v_pk_fma_f32 v[110:111], v[110:111], v[186:187], v[204:205] op_sel:[0,0,1] op_sel_hi:[1,1,0]
	ds_bpermute_b32 v94, v169, v95
	ds_bpermute_b32 v98, v131, v95
	ds_bpermute_b32 v100, v170, v95
	ds_bpermute_b32 v102, v129, v95
	ds_bpermute_b32 v95, v169, v103
	ds_bpermute_b32 v112, v169, v104
	ds_bpermute_b32 v113, v169, v110
	ds_bpermute_b32 v99, v131, v103
	ds_bpermute_b32 v200, v131, v104
	ds_bpermute_b32 v201, v131, v110
	ds_bpermute_b32 v101, v170, v103
	ds_bpermute_b32 v202, v170, v104
	ds_bpermute_b32 v203, v170, v110
	ds_bpermute_b32 v103, v129, v103
	ds_bpermute_b32 v104, v129, v104
	ds_bpermute_b32 v105, v129, v110
	s_waitcnt lgkmcnt(9)
	v_pk_fma_f32 v[94:95], v[114:115], v[94:95], v[112:113]
	s_nop 0
	v_cndmask_b32_e64 v93, v114, v94, s[50:51]
	s_waitcnt lgkmcnt(6)
	v_pk_fma_f32 v[98:99], v[94:95], v[98:99], v[200:201]
	v_cndmask_b32_e64 v97, v115, v95, s[50:51]
	v_cndmask_b32_e64 v93, v93, v98, s[52:53]
	s_waitcnt lgkmcnt(3)
	v_pk_fma_f32 v[94:95], v[98:99], v[100:101], v[202:203]
	v_cndmask_b32_e64 v97, v97, v99, s[52:53]
	v_cndmask_b32_e64 v93, v93, v94, s[54:55]
	s_waitcnt lgkmcnt(0)
	v_pk_fma_f32 v[114:115], v[94:95], v[102:103], v[104:105]
	v_cndmask_b32_e64 v94, v97, v95, s[54:55]
	v_cndmask_b32_e64 v93, v93, v114, s[48:49]
	v_cndmask_b32_e64 v94, v94, v115, s[48:49]
	v_fmac_f32_e32 v189, v180, v93
	v_fmac_f32_e32 v191, v92, v94
	v_fmac_f32_e32 v192, v175, v189
	v_fmac_f32_e32 v108, v183, v191
	v_fmac_f32_e32 v198, v177, v192
	v_fmac_f32_e32 v106, v185, v108
	v_fmac_f32_e32 v172, v179, v198
	ds_write_b32 v206, v189
	ds_write_b32 v209, v191
	ds_write_b32 v207, v192
	ds_write_b32 v210, v108
	ds_write_b32 v208, v198
	ds_write_b32 v211, v106
	v_fmac_f32_e32 v204, v187, v106
	ds_write_b32 v195, v172
	ds_write_b32 v117, v204
	s_cbranch_scc1 .LBB0_598
	s_mov_b64 s[14:15], 0
